# GLA64 segment-prefix: 32 v_cndmask replaced by exec-masked accumulate (16 SALU), on top of v008
# speedup vs baseline: 1.0070x; 1.0070x over previous
; __device__ __forceinline__ unsigned pk2(float lo, float hi) { const f32x2_t v = {lo, hi}; return __builtin_bit_cast(unsigned, __builtin_convertvector(v, bf16x2_t)); }
; #define LDS_BARRIER() do { asm volatile("s_waitcnt lgkmcnt(0)" ::: "memory"); __builtin_amdgcn_s_barrier(); asm volatile("" ::: "memory"); } while (0)
; __device__ __forceinline__ f32x2 ex2v(f32x2 x) { f32x2 r; r.x = __builtin_amdgcn_exp2f(x.x); r.y = __builtin_amdgcn_exp2f(x.y); return r; }
; template <int DKH, int DVW>
; __device__ __forceinline__ void gla_chain(const Params& p, int jl, unsigned char* lds, int seq, int h, int e, int dk0, int dv0, bf16_t* OUTB, int ostride, int orow_off) {
;     ...
;             LDS_BARRIER();
;             f32x2 off = (f32x2){0.f, 0.f}, tot = (f32x2){0.f, 0.f};
; #pragma unroll
;             for (int s = 0; s < NSEG; ++s) { const f32x2 sv = *(const f32x2*)(segtot + s * DKH + 2 * dkp); tot += sv; const bool inc = e == 0 ? (s < seg) : (s > seg); off += inc ? sv : (f32x2){0.f, 0.f}; }
;             const f32x2 dec = ex2v(tot);
;             if (seg == 0) *(f32x2*)(decs + 2 * dkp) = dec;
;             f32x2 ke[NP];
; #pragma unroll
;             for (int i = 0; i < NP; ++i) { const f32x2 b = bl[i] + off; const f32x2 eb = ex2v(b), enb = ex2v(-b);
;                 const f32x2 qf = (f32x2){__uint_as_float(qraw[i] << 16), __uint_as_float(qraw[i] & 0xffff0000u)} * QSCALE * eb;
;                 const f32x2 kf = (f32x2){__uint_as_float(kraw[i] << 16), __uint_as_float(kraw[i] & 0xffff0000u)} * enb;
;                 *(unsigned*)(qd + (seg * NP + i) * 272 + dkp * 4) = pk2(qf.x, qf.y);
;                 *(unsigned*)(kd + (seg * NP + i) * 272 + dkp * 4) = pk2(kf.x, kf.y);
;                 ke[i] = kf * dec; }
.LBB0_347:
	ds_write_b64 v84, v[34:35] offset:8192
	s_waitcnt lgkmcnt(0)
	s_barrier
	v_add_u32_e32 v32, 0x2000, v86
	ds_read2_b64 v[58:61], v32 offset1:32
	ds_read2_b64 v[54:57], v32 offset0:64 offset1:96
	ds_read2_b64 v[50:53], v32 offset0:128 offset1:160
	ds_read2_b64 v[46:49], v32 offset0:192 offset1:224
	v_add_u32_e32 v32, 0x2800, v86
	s_waitcnt lgkmcnt(3)
	v_pk_add_f32 v[78:79], v[58:59], 0 op_sel_hi:[1,0]
	ds_read2_b64 v[42:45], v32 offset1:32
	v_pk_add_f32 v[30:31], v[78:79], v[60:61]
	ds_read2_b64 v[38:41], v32 offset0:64 offset1:96
	s_waitcnt lgkmcnt(4)
	v_pk_add_f32 v[30:31], v[30:31], v[54:55]
	ds_read2_b64 v[34:37], v32 offset0:128 offset1:160
	v_pk_add_f32 v[30:31], v[30:31], v[56:57]
	s_waitcnt lgkmcnt(4)
	v_pk_add_f32 v[30:31], v[30:31], v[50:51]
	s_nop 0
	v_pk_add_f32 v[30:31], v[30:31], v[52:53]
	s_waitcnt lgkmcnt(3)
	v_pk_add_f32 v[30:31], v[30:31], v[46:47]
	s_nop 0
	v_pk_add_f32 v[30:31], v[30:31], v[48:49]
	s_waitcnt lgkmcnt(2)
	v_pk_add_f32 v[30:31], v[30:31], v[42:43]
	s_nop 0
	v_pk_add_f32 v[58:59], v[30:31], v[44:45]
	ds_read2_b64 v[30:33], v32 offset0:192 offset1:224
	s_waitcnt lgkmcnt(2)
	v_pk_add_f32 v[58:59], v[58:59], v[38:39]
	s_nop 0
	v_pk_add_f32 v[58:59], v[58:59], v[40:41]
	s_waitcnt lgkmcnt(1)
	v_pk_add_f32 v[58:59], v[58:59], v[34:35]
	s_nop 0
	v_pk_add_f32 v[58:59], v[58:59], v[36:37]
	s_waitcnt lgkmcnt(0)
	v_pk_add_f32 v[58:59], v[58:59], v[30:31]
	s_nop 0
	v_pk_add_f32 v[58:59], v[58:59], v[32:33]
	s_nop 0
	v_exp_f32_e32 v58, v58
	v_exp_f32_e32 v59, v59
	s_and_saveexec_b64 s[90:91], s[36:37]
	ds_write_b64 v86, v[58:59] offset:12288
	s_or_b64 exec, exec, s[90:91]
	s_mov_b64 s[98:99], exec
	v_mov_b32_e32 v234, 0
	v_mov_b32_e32 v235, 0
	s_and_b64 exec, s[98:99], s[40:41]
	v_pk_add_f32 v[234:235], v[234:235], v[78:79]
	s_and_b64 exec, s[98:99], s[42:43]
	v_pk_add_f32 v[234:235], v[234:235], v[60:61]
	s_and_b64 exec, s[98:99], s[44:45]
	v_pk_add_f32 v[234:235], v[234:235], v[54:55]
	s_and_b64 exec, s[98:99], s[46:47]
	v_pk_add_f32 v[234:235], v[234:235], v[56:57]
	s_and_b64 exec, s[98:99], s[48:49]
	v_pk_add_f32 v[234:235], v[234:235], v[50:51]
	s_and_b64 exec, s[98:99], s[50:51]
	v_pk_add_f32 v[234:235], v[234:235], v[52:53]
	s_and_b64 exec, s[98:99], s[52:53]
	v_pk_add_f32 v[234:235], v[234:235], v[46:47]
	s_and_b64 exec, s[98:99], s[54:55]
	v_pk_add_f32 v[234:235], v[234:235], v[48:49]
	s_and_b64 exec, s[98:99], s[56:57]
	v_pk_add_f32 v[234:235], v[234:235], v[42:43]
	s_and_b64 exec, s[98:99], s[58:59]
	v_pk_add_f32 v[234:235], v[234:235], v[44:45]
	s_and_b64 exec, s[98:99], s[60:61]
	v_pk_add_f32 v[234:235], v[234:235], v[38:39]
	s_and_b64 exec, s[98:99], s[62:63]
	v_pk_add_f32 v[234:235], v[234:235], v[40:41]
	s_and_b64 exec, s[98:99], s[64:65]
	v_pk_add_f32 v[234:235], v[234:235], v[34:35]
	s_and_b64 exec, s[98:99], s[84:85]
	v_pk_add_f32 v[234:235], v[234:235], v[36:37]
	s_and_b64 exec, s[98:99], s[86:87]
	v_pk_add_f32 v[234:235], v[234:235], v[30:31]
	s_and_b64 exec, s[98:99], s[88:89]
	v_pk_add_f32 v[234:235], v[234:235], v[32:33]
	s_mov_b64 exec, s[98:99]
	v_mov_b32_e32 v30, v234
	v_mov_b32_e32 v31, v235
	s_waitcnt vmcnt(9)
	v_lshlrev_b32_e32 v36, 16, v109
	v_pk_add_f32 v[32:33], v[70:71], v[30:31]
	v_and_b32_e32 v37, 0xffff0000, v109
	v_exp_f32_e32 v34, v32
	v_exp_f32_e32 v35, v33
	v_exp_f32_e64 v32, -v32
	v_exp_f32_e64 v33, -v33
	v_pk_mul_f32 v[36:37], v[36:37], s[28:29] op_sel_hi:[1,0]
	s_waitcnt vmcnt(7)
	v_lshlrev_b32_e32 v38, 16, v107
	v_pk_mul_f32 v[34:35], v[36:37], v[34:35]
	v_lshlrev_b32_e32 v36, 16, v108
	v_and_b32_e32 v37, 0xffff0000, v108
	v_cvt_pk_bf16_f32 v40, v34, v35
	v_pk_add_f32 v[34:35], v[76:77], v[30:31]
	v_pk_mul_f32 v[32:33], v[32:33], v[36:37]
	v_exp_f32_e32 v36, v34
	v_exp_f32_e32 v37, v35
	v_exp_f32_e64 v34, -v34
	v_exp_f32_e64 v35, -v35
	v_and_b32_e32 v39, 0xffff0000, v107
	v_pk_mul_f32 v[38:39], v[38:39], s[28:29] op_sel_hi:[1,0]
	v_add_u32_e32 v42, 0x3400, v94
	v_pk_mul_f32 v[36:37], v[38:39], v[36:37]
	s_waitcnt vmcnt(6)
	v_lshlrev_b32_e32 v38, 16, v106
	v_and_b32_e32 v39, 0xffff0000, v106
	v_pk_mul_f32 v[34:35], v[34:35], v[38:39]
	v_cvt_pk_bf16_f32 v36, v36, v37
	v_cvt_pk_bf16_f32 v41, v32, v33
	ds_write2_b32 v42, v40, v36 offset1:68
	v_cvt_pk_bf16_f32 v36, v34, v35
	v_add_u32_e32 v43, 0x7800, v94
	ds_write2_b32 v43, v41, v36 offset1:68
	v_pk_add_f32 v[36:37], v[74:75], v[30:31]
	s_waitcnt vmcnt(5)
	v_lshlrev_b32_e32 v40, 16, v105
	v_exp_f32_e32 v38, v36
	v_exp_f32_e32 v39, v37
	v_and_b32_e32 v41, 0xffff0000, v105
	v_exp_f32_e64 v36, -v36
	v_exp_f32_e64 v37, -v37
	v_pk_mul_f32 v[40:41], v[40:41], s[28:29] op_sel_hi:[1,0]
	v_pk_add_f32 v[30:31], v[72:73], v[30:31]
	v_pk_mul_f32 v[38:39], v[40:41], v[38:39]
	s_waitcnt vmcnt(4)
	v_lshlrev_b32_e32 v40, 16, v104
	v_cvt_pk_bf16_f32 v44, v38, v39
	v_exp_f32_e32 v38, v30
	v_exp_f32_e32 v39, v31
	v_and_b32_e32 v41, 0xffff0000, v104
	v_exp_f32_e64 v30, -v30
	v_exp_f32_e64 v31, -v31
	v_pk_mul_f32 v[36:37], v[36:37], v[40:41]
	s_waitcnt vmcnt(3)
	v_lshlrev_b32_e32 v40, 16, v103
	v_and_b32_e32 v41, 0xffff0000, v103
	v_pk_mul_f32 v[40:41], v[40:41], s[28:29] op_sel_hi:[1,0]
	v_pk_mul_f32 v[32:33], v[58:59], v[32:33]
	v_pk_mul_f32 v[38:39], v[40:41], v[38:39]
	s_waitcnt vmcnt(2)
	v_lshlrev_b32_e32 v40, 16, v102
	v_and_b32_e32 v41, 0xffff0000, v102
	v_pk_mul_f32 v[30:31], v[30:31], v[40:41]
	v_cvt_pk_bf16_f32 v38, v38, v39
	v_pk_mul_f32 v[34:35], v[58:59], v[34:35]
	v_cvt_pk_bf16_f32 v45, v36, v37
	v_pk_mul_f32 v[36:37], v[58:59], v[36:37]
	ds_write2_b32 v42, v44, v38 offset0:136 offset1:204
	v_cvt_pk_bf16_f32 v38, v30, v31
	v_pk_mul_f32 v[30:31], v[58:59], v[30:31]
	ds_write2_b32 v43, v45, v38 offset0:136 offset1:204
	v_cvt_pk_bf16_f32 v38, v32, v34
	v_cvt_pk_bf16_f32 v39, v36, v30
	v_cvt_pk_bf16_f32 v30, v33, v35
	v_cvt_pk_bf16_f32 v31, v37, v31
	ds_write2_b64 v100, v[38:39], v[30:31] offset0:128 offset1:146
	s_waitcnt vmcnt(0)
; __device__ __forceinline__ unsigned pk2(float lo, float hi) { const f32x2_t v = {lo, hi}; return __builtin_bit_cast(unsigned, __builtin_convertvector(v, bf16x2_t)); }
; #define LDS_BARRIER() do { asm volatile("s_waitcnt lgkmcnt(0)" ::: "memory"); __builtin_amdgcn_s_barrier(); asm volatile("" ::: "memory"); } while (0)
; template <int DKH, int DVW>
; __device__ __forceinline__ void gla_chain(const Params& p, int jl, unsigned char* lds, int seq, int h, int e, int dk0, int dv0, bf16_t* OUTB, int ostride, int orow_off) {
;     ...
; #pragma unroll
;             for (int jv = 0; jv < NV; ++jv) { const unsigned wd[4] = {vraw[jv].x, vraw[jv].y, vraw[jv].z, vraw[jv].w};
; #pragma unroll
;                 for (int k2 = 0; k2 < 4; ++k2) { const unsigned r = wd[k2], q = (unsigned)__builtin_amdgcn_mov_dpp((int)r, 0xB1, 0xf, 0xf, true);
;                     const bool odd = (lane & 1) != 0;
;                     const unsigned word = odd ? ((q >> 16) | (r & 0xffff0000u)) : ((r & 0xffffu) | (q << 16));
;                     *(unsigned*)(vTw + (jv * 8 + 2 * k2 + (odd ? 1 : 0)) * 144 + (lane >> 1) * 4) = word; } }
;             LDS_BARRIER();
;             { const int st = wave >> 1, ct0 = (wave & 1) * 2;
;               bf16x8 Af[KS], Bf[2][KS];
; #pragma unroll
;               for (int ks = 0; ks < KS; ++ks) { Af[ks] = *(const bf16x8*)(kd + (st * 16 + fr) * 272 + (ks * 32 + fq * 8) * 2);
;                   Bf[0][ks] = *(const bf16x8*)(qd + (ct0 * 16 + fr) * 272 + (ks * 32 + fq * 8) * 2); Bf[1][ks] = *(const bf16x8*)(qd + ((ct0 + 1) * 16 + fr) * 272 + (ks * 32 + fq * 8) * 2); }
;               __builtin_amdgcn_sched_barrier(0);
;               f32x4 a0 = (f32x4){0.f, 0.f, 0.f, 0.f}, a1 = a0;
; #pragma unroll
;               for (int ks = 0; ks < KS; ++ks) { a0 = __builtin_amdgcn_mfma_f32_16x16x32_bf16(Af[ks], Bf[0][ks], a0, 0, 0, 0); a1 = __builtin_amdgcn_mfma_f32_16x16x32_bf16(Af[ks], Bf[1][ks], a1, 0, 0, 0); }
;               const int sb = st * 16 + fq * 4;
; #pragma unroll
;               for (int tix = 0; tix < 2; ++tix) { const int c = (ct0 + tix) * 16 + fr; f32x4 a = tix == 0 ? a0 : a1;
; #pragma unroll
;                   for (int i = 0; i < 4; ++i) { const bool keep = e == 0 ? (sb + i <= c) : (sb + i > c); a[i] = keep ? a[i] : 0.f; }
;                   u32x2 w; w.x = pk2(a[0], a[1]); w.y = pk2(a[2], a[3]);
;                   *(u32x2*)(sc + c * 144 + sb * 2) = w; } }
	v_mov_b32_dpp v31, v26 quad_perm:[1,0,3,2] row_mask:0xf bank_mask:0xf bound_ctrl:1
	v_perm_b32 v30, v31, v26, v254
	ds_write_b32 v101, v30
	v_mov_b32_dpp v30, v27 quad_perm:[1,0,3,2] row_mask:0xf bank_mask:0xf bound_ctrl:1
	v_perm_b32 v26, v30, v27, v254
	v_mov_b32_dpp v27, v28 quad_perm:[1,0,3,2] row_mask:0xf bank_mask:0xf bound_ctrl:1
	ds_write_b32 v101, v26 offset:288
	v_perm_b32 v26, v27, v28, v254
	ds_write_b32 v101, v26 offset:576
	v_mov_b32_dpp v26, v29 quad_perm:[1,0,3,2] row_mask:0xf bank_mask:0xf bound_ctrl:1
	v_perm_b32 v30, v26, v29, v254
	v_mov_b32_dpp v27, v22 quad_perm:[1,0,3,2] row_mask:0xf bank_mask:0xf bound_ctrl:1
	ds_write_b32 v101, v30 offset:864
	v_perm_b32 v26, v27, v22, v254
	ds_write_b32 v101, v26 offset:1152
	v_mov_b32_dpp v26, v23 quad_perm:[1,0,3,2] row_mask:0xf bank_mask:0xf bound_ctrl:1
	v_perm_b32 v22, v26, v23, v254
	v_mov_b32_dpp v23, v24 quad_perm:[1,0,3,2] row_mask:0xf bank_mask:0xf bound_ctrl:1
	ds_write_b32 v101, v22 offset:1440
	v_perm_b32 v22, v23, v24, v254
	ds_write_b32 v101, v22 offset:1728
	v_mov_b32_dpp v22, v25 quad_perm:[1,0,3,2] row_mask:0xf bank_mask:0xf bound_ctrl:1
	v_perm_b32 v26, v22, v25, v254
	ds_write_b32 v101, v26 offset:2016
	s_waitcnt lgkmcnt(0)
	s_barrier
	ds_read_b128 v[22:25], v95 offset:30720
	ds_read_b128 v[26:29], v95 offset:30784
	ds_read_b128 v[30:33], v96 offset:13312
	ds_read_b128 v[34:37], v96 offset:13376
	ds_read_b128 v[38:41], v96 offset:17664
	ds_read_b128 v[42:45], v96 offset:17728
	s_waitcnt lgkmcnt(3)
	v_mfma_f32_16x16x32_bf16 v[30:33], v[22:25], v[30:33], 0
	v_add_u32_e32 v58, v88, v93
	v_add_u32_e32 v78, 0x3000, v99
	v_add_u32_e32 v79, 0x4000, v99
	s_waitcnt lgkmcnt(1)
	v_mfma_f32_16x16x32_bf16 v[22:25], v[22:25], v[38:41], 0
	v_add_u32_e32 v118, 0x5000, v99
	v_add_u32_e32 v119, 0x6000, v99
	v_cvt_pk_bf16_f32 v70, v6, v7
	v_mfma_f32_16x16x32_bf16 v[30:33], v[26:29], v[34:37], v[30:33]
	v_add_u32_e32 v34, v88, v87
	v_cvt_pk_bf16_f32 v71, v8, v9
	v_cvt_pk_bf16_f32 v72, v10, v11
	s_waitcnt lgkmcnt(0)
	v_mfma_f32_16x16x32_bf16 v[22:25], v[26:29], v[42:45], v[22:25]
	v_cvt_pk_bf16_f32 v73, v12, v13
	s_nop 1
	v_cndmask_b32_e64 v30, 0, v30, s[66:67]
	v_cndmask_b32_e64 v31, 0, v31, s[68:69]
	v_cndmask_b32_e64 v32, 0, v32, s[70:71]
	v_cndmask_b32_e64 v33, 0, v33, s[72:73]
	s_nop 0
	v_cndmask_b32_e64 v22, 0, v22, s[76:77]
	v_cndmask_b32_e64 v23, 0, v23, s[78:79]
	v_cndmask_b32_e64 v24, 0, v24, s[80:81]
	v_cndmask_b32_e64 v25, 0, v25, s[82:83]
	v_cvt_pk_bf16_f32 v30, v30, v31
	v_cvt_pk_bf16_f32 v31, v32, v33
	v_cvt_pk_bf16_f32 v22, v22, v23
	v_cvt_pk_bf16_f32 v23, v24, v25
	ds_write_b64 v97, v[30:31]
	ds_write_b64 v97, v[22:23] offset:2304
	s_waitcnt lgkmcnt(0)
	s_barrier
; template <int DKH, int DVW>
; __device__ __forceinline__ void gla_chain(const Params& p, int jl, unsigned char* lds, int seq, int h, int e, int dk0, int dv0, bf16_t* OUTB, int ostride, int orow_off) {
;     ...
;                 for (int ks = 0; ks < 2; ++ks) vf[dt][ks] = *(const bf16x8*)(vTw + (dt * 16 + fr) * 144 + (ks * 32 + fq * 8) * 2);
;             f32x4 o[DT][4];
;             { bf16x8 Bs[2][4];
; #pragma unroll
;               for (int ks = 0; ks < 2; ++ks)
; #pragma unroll
;                   for (int ct = 0; ct < 4; ++ct) Bs[ks][ct] = *(const bf16x8*)(sc + (ct * 16 + fr) * 144 + (ks * 32 + fq * 8) * 2);
;               bf16x8 Sbf[KS][DT];
; #pragma unroll
;               for (int ks = 0; ks < KS; ++ks)
; #pragma unroll
;                   for (int dt = 0; dt < DT; ++dt) { const f32x4 x0 = Sacc[2 * ks][dt], x1 = Sacc[2 * ks + 1][dt];
;                       const u32x4 w = (u32x4){pk2(x0[0], x0[1]), pk2(x0[2], x0[3]), pk2(x1[0], x1[1]), pk2(x1[2], x1[3])}; Sbf[ks][dt] = __builtin_bit_cast(bf16x8, w); }
;               u32x4 Bq[2][4];
;     ...
;               GLA_LDQ(0, 0);
;               __builtin_amdgcn_sched_barrier(0);
; #pragma unroll
;               for (int ct = 0; ct < 4; ++ct)
; #pragma unroll
;                   for (int dt = 0; dt < DT; ++dt) o[dt][ct] = __builtin_amdgcn_mfma_f32_16x16x32_bf16(vf[dt][0], Bs[0][ct], (f32x4){0.f, 0.f, 0.f, 0.f}, 0, 0, 0);
; #pragma unroll
;               for (int ct = 0; ct < 4; ++ct)
; #pragma unroll
;                   for (int dt = 0; dt < DT; ++dt) o[dt][ct] = __builtin_amdgcn_mfma_f32_16x16x32_bf16(vf[dt][1], Bs[1][ct], o[dt][ct], 0, 0, 0);
; #pragma unroll
;               for (int ks = 0; ks < KS; ++ks) {
;                   if (ks < KS - 1) GLA_LDQ((ks + 1) & 1, ks + 1);
;                   __builtin_amdgcn_sched_barrier(0);
; #pragma unroll
;                   for (int ct = 0; ct < 4; ++ct) { const bf16x8 B = __builtin_bit_cast(bf16x8, Bq[ks & 1][ct]);
; #pragma unroll
;                       for (int dt = 0; dt < DT; ++dt) o[dt][ct] = __builtin_amdgcn_mfma_f32_16x16x32_bf16(Sbf[ks][dt], B, o[dt][ct], 0, 0, 0); }
;                   __builtin_amdgcn_sched_barrier(0);
;               }
;     ...
;             }
; #pragma unroll
;             for (int ct = 0; ct < 4; ++ct)
; #pragma unroll
;                 for (int dt = 0; dt < DT; ++dt) { u32x2 w; w.x = pk2(o[dt][ct][0], o[dt][ct][1]); w.y = pk2(o[dt][ct][2], o[dt][ct][3]);
	ds_read_b128 v[22:25], v98
	ds_read_b128 v[26:29], v98 offset:64
	ds_read_b128 v[30:33], v34
	ds_read_b128 v[34:37], v34 offset:64
	ds_read_b128 v[38:41], v58
	ds_read_b128 v[42:45], v58 offset:64
	ds_read_b128 v[46:49], v58 offset:2304
	ds_read_b128 v[50:53], v58 offset:2368
	ds_read_b128 v[54:57], v58 offset:4608
	ds_read_b128 v[58:61], v58 offset:4672
	ds_read2_b64 v[74:77], v78 offset0:128 offset1:132
	ds_read2_b64 v[102:105], v79 offset0:160 offset1:164
	ds_read2_b64 v[106:109], v118 offset0:192 offset1:196
	ds_read2_b64 v[110:113], v119 offset0:224 offset1:228
	v_cvt_pk_bf16_f32 v114, v14, v15
	v_cvt_pk_bf16_f32 v115, v16, v17
	v_cvt_pk_bf16_f32 v116, v18, v19
	v_cvt_pk_bf16_f32 v117, v20, v21
	s_waitcnt lgkmcnt(11)
	v_mfma_f32_16x16x32_bf16 v[30:33], v[22:25], v[30:33], 0
	s_waitcnt lgkmcnt(9)
	v_mfma_f32_16x16x32_bf16 v[38:41], v[22:25], v[38:41], 0
	s_waitcnt lgkmcnt(7)
	v_mfma_f32_16x16x32_bf16 v[46:49], v[22:25], v[46:49], 0
	s_waitcnt lgkmcnt(5)
	v_mfma_f32_16x16x32_bf16 v[54:57], v[22:25], v[54:57], 0
	v_mfma_f32_16x16x32_bf16 v[30:33], v[26:29], v[34:37], v[30:33]
	v_mfma_f32_16x16x32_bf16 v[34:37], v[26:29], v[42:45], v[38:41]
	v_mfma_f32_16x16x32_bf16 v[38:41], v[26:29], v[50:53], v[46:49]
	s_waitcnt lgkmcnt(4)
	v_mfma_f32_16x16x32_bf16 v[42:45], v[26:29], v[58:61], v[54:57]
	s_nop 0
	ds_read2_b64 v[46:49], v78 offset0:136 offset1:140
	ds_read2_b64 v[50:53], v79 offset0:168 offset1:172
	ds_read2_b64 v[54:57], v118 offset0:200 offset1:204
	ds_read2_b64 v[58:61], v119 offset0:232 offset1:236
	s_waitcnt lgkmcnt(7)
	v_mfma_f32_16x16x32_bf16 v[30:33], v[70:73], v[74:77], v[30:33]
	s_waitcnt lgkmcnt(6)
	v_mfma_f32_16x16x32_bf16 v[34:37], v[70:73], v[102:105], v[34:37]
	s_waitcnt lgkmcnt(5)
	v_mfma_f32_16x16x32_bf16 v[38:41], v[70:73], v[106:109], v[38:41]
	s_waitcnt lgkmcnt(4)
	v_mfma_f32_16x16x32_bf16 v[42:45], v[70:73], v[110:113], v[42:45]
	s_waitcnt lgkmcnt(3)
	v_mfma_f32_16x16x32_bf16 v[30:33], v[114:117], v[46:49], v[30:33]
	s_waitcnt lgkmcnt(2)
	v_mfma_f32_16x16x32_bf16 v[34:37], v[114:117], v[50:53], v[34:37]
	s_waitcnt lgkmcnt(1)
	v_mfma_f32_16x16x32_bf16 v[38:41], v[114:117], v[54:57], v[38:41]
	s_waitcnt lgkmcnt(0)
	v_mfma_f32_16x16x32_bf16 v[42:45], v[114:117], v[58:61], v[42:45]
	v_add_u32_e32 v46, s96, v90
	v_ashrrev_i32_e32 v47, 31, v46
	v_cvt_pk_bf16_f32 v30, v30, v31
	v_cvt_pk_bf16_f32 v31, v32, v33
	v_lshlrev_b64 v[32:33], s34, v[46:47]
	v_lshl_add_u64 v[32:33], v[32:33], 1, v[68:69]
	global_store_dwordx2 v[32:33], v[30:31], off
	v_or_b32_e32 v32, 16, v46
	v_ashrrev_i32_e32 v33, 31, v32
	v_lshlrev_b64 v[32:33], s34, v[32:33]
	v_cvt_pk_bf16_f32 v30, v34, v35
	v_cvt_pk_bf16_f32 v31, v36, v37
	v_lshl_add_u64 v[32:33], v[32:33], 1, v[68:69]
	global_store_dwordx2 v[32:33], v[30:31], off
	v_or_b32_e32 v32, 32, v46
	v_ashrrev_i32_e32 v33, 31, v32
	v_lshlrev_b64 v[32:33], s34, v[32:33]
	v_cvt_pk_bf16_f32 v30, v38, v39
	v_cvt_pk_bf16_f32 v31, v40, v41
	v_lshl_add_u64 v[32:33], v[32:33], 1, v[68:69]
	global_store_dwordx2 v[32:33], v[30:31], off
	v_or_b32_e32 v32, 48, v46
	v_ashrrev_i32_e32 v33, 31, v32
	v_lshlrev_b64 v[32:33], s34, v[32:33]
	v_cvt_pk_bf16_f32 v30, v42, v43
	v_cvt_pk_bf16_f32 v31, v44, v45
	v_lshl_add_u64 v[32:33], v[32:33], 1, v[68:69]
	global_store_dwordx2 v[32:33], v[30:31], off
	v_add_u32_e32 v74, v89, v0
	v_add_u32_e32 v38, v91, v87
	v_add_u32_e32 v78, v91, v93
	ds_read_b128 v[30:33], v74 offset:12288
	ds_read_b128 v[34:37], v38 offset:48128
	ds_read_b128 v[38:41], v38 offset:48192
	ds_read_b128 v[42:45], v74 offset:12352
	ds_read_b128 v[46:49], v78 offset:48128
	ds_read_b128 v[50:53], v78 offset:48192
	ds_read_b128 v[54:57], v74 offset:12416
	ds_read_b128 v[58:61], v78 offset:50432
	ds_read_b128 v[70:73], v78 offset:50496
	ds_read_b128 v[74:77], v74 offset:12480
	ds_read_b128 v[102:105], v78 offset:52736
	ds_read_b128 v[106:109], v78 offset:52800
	s_waitcnt lgkmcnt(11)
	v_pk_mul_f32 v[6:7], v[6:7], v[30:31]
	v_pk_mul_f32 v[8:9], v[8:9], v[32:33]
	s_waitcnt lgkmcnt(8)
	v_pk_mul_f32 v[10:11], v[10:11], v[42:43]
	v_pk_mul_f32 v[12:13], v[12:13], v[44:45]
	v_mfma_f32_16x16x32_bf16 v[6:9], v[34:37], v[22:25], v[6:9]
	s_waitcnt lgkmcnt(7)
	v_mfma_f32_16x16x32_bf16 v[10:13], v[46:49], v[22:25], v[10:13]
	v_mfma_f32_16x16x32_bf16 v[6:9], v[38:41], v[26:29], v[6:9]
	s_waitcnt lgkmcnt(6)
	v_mfma_f32_16x16x32_bf16 v[10:13], v[50:53], v[26:29], v[10:13]
	s_waitcnt lgkmcnt(5)
	v_pk_mul_f32 v[14:15], v[14:15], v[54:55]
	v_pk_mul_f32 v[16:17], v[16:17], v[56:57]
	s_waitcnt lgkmcnt(2)
	v_pk_mul_f32 v[18:19], v[18:19], v[74:75]
	v_pk_mul_f32 v[20:21], v[20:21], v[76:77]
	v_mfma_f32_16x16x32_bf16 v[14:17], v[58:61], v[22:25], v[14:17]
	s_waitcnt lgkmcnt(1)
	v_mfma_f32_16x16x32_bf16 v[18:21], v[102:105], v[22:25], v[18:21]
	v_mfma_f32_16x16x32_bf16 v[14:17], v[70:73], v[26:29], v[14:17]
	s_waitcnt lgkmcnt(0)
	v_mfma_f32_16x16x32_bf16 v[18:21], v[106:109], v[26:29], v[18:21]
	s_and_saveexec_b64 s[90:91], s[2:3]
	s_cbranch_execz .LBB0_339
	s_and_b32 s2, s35, 0x400
	v_lshl_add_u32 v22, s2, 2, v92
	ds_write_b128 v22, v[2:5]
	s_branch .LBB0_339
